# rwa token quotas re-tuned with per-phase probes to 6/10/10 per wave (classes 0-95 / 96-239 / 240-255), rwb staging loads issued with the weight loads, rwb wave stagger 12
# speedup vs baseline: 1.0015x; 1.0015x over previous
; __device__ __forceinline__ int ltid(int wvs) { int t = (wvs << 6) | (int)__builtin_amdgcn_mbcnt_hi(~0u, __builtin_amdgcn_mbcnt_lo(~0u, 0u)); asm volatile("" : "+v"(t)); return t; }
; __device__ __forceinline__ int lbid() { int b = __builtin_amdgcn_workgroup_id_x(); asm volatile("" : "+s"(b)); return b; }
; __device__ __forceinline__ void phase_rwa(const int wvs, const Params& p, int layer) {
;   const int lane = ltid(wvs) & 63, gw = lbid() * 8 + (ltid(wvs) >> 6);
;   hf* P = (hf*)(p.ws + OFF_BIG); hf* RL1 = (hf*)(p.ws + OFF_RL1); hf* RL3 = (hf*)(p.ws + OFF_RL3); float* INVN = (float*)(p.ws + OFF_INVN);
;   const float* mu = p.in[I_MU] + layer * 1536; const float* kkw = p.in[I_KK] + layer * 384;
;   int t0, tq;
;   if (gw < 768) { t0 = 3 * gw; tq = 3; } else if (gw < 1920) { t0 = 2304 + 11 * (gw - 768); tq = 11; } else { t0 = 14976 + 19 * (gw - 1920); tq = 19; }
.LBB0_1037:
	s_mov_b64 s[2:3], s[0:1]
	s_load_dwordx2 s[6:7], s[2:3], 0xc8
	s_load_dwordx2 s[4:5], s[2:3], 0xf8
	s_load_dwordx2 s[20:21], s[2:3], 0x138
	v_mov_b32_e32 v0, v193
	s_mov_b32 s2, s28
	v_mov_b32_e32 v2, v193
	s_nop 0
	v_ashrrev_i32_e32 v2, 6, v2
	v_lshl_add_u32 v2, s2, 3, v2
	s_movk_i32 s2, 0x2ff
	v_cmp_lt_i32_e32 vcc, s2, v2
	s_and_saveexec_b64 s[2:3], vcc
	s_xor_b64 s[8:9], exec, s[2:3]
	s_cbranch_execz .LBB0_1043
	s_movk_i32 s2, 0x77f
	v_cmp_lt_u32_e32 vcc, s2, v2
	s_and_saveexec_b64 s[2:3], vcc
	s_xor_b64 s[10:11], exec, s[2:3]
	v_mov_b32_e32 v4, 0xfffff400
	v_mov_b32_e32 v5, -1
	v_mad_u64_u32 v[78:79], s[2:3], v2, 10, v[4:5]
	s_or_saveexec_b64 s[10:11], s[10:11]
	v_mov_b32_e32 v4, 10
	s_xor_b64 exec, exec, s[10:11]
	v_mov_b32_e32 v6, 0xfffff400
	v_mov_b32_e32 v7, -1
	v_mov_b32_e32 v4, 10
	v_mad_u64_u32 v[78:79], s[2:3], v2, 10, v[6:7]
	s_or_b64 exec, exec, s[10:11]

; __device__ __forceinline__ float tanhf_(float x) { const float e = __expf(2.0f * fminf(fmaxf(x, -15.f), 15.f)); return (e - 1.0f) * __builtin_amdgcn_rcpf(e + 1.0f); }
; __device__ __forceinline__ void phase_rwb(const int wvs, const Params& p, LAS unsigned char* lds, int layer) {
;     ...
;   for (int d = 0; d < 2; ++d) {
;     h8 bw[2], ba[2];
; #pragma unroll
;     for (int ks = 0; ks < 2; ++ks) { const h8 x = *(const h8*)(P + tok * PP + PC_RL2 + d * 64 + ks * 32 + fq * 8);
; #pragma unroll
;       for (int j = 0; j < 8; ++j) bw[ks][j] = (hf)tanhf_((float)x[j]);
;       ba[ks] = *(const h8*)(P + tok * PP + PC_RL2 + 128 + d * 64 + ks * 32 + fq * 8); }
;     { h8 sw[6], sa[6];
; #pragma unroll
;       for (int j = 0; j < 6; ++j) { const int idx = tid + 512 * j; const size_t wo = ((size_t)d * 384 + (idx >> 3)) * 64 + (idx & 7) * 8; sw[j] = *(const h8*)(wupT + wo); sa[j] = *(const h8*)(aupT + wo); }
.LBB0_1145:
	s_lshl_b32 s30, s6, 7
	v_lshl_add_u64 v[14:15], v[66:67], 0, s[30:31]
	global_load_dwordx4 v[2:5], v[14:15], off offset:3584
	s_mul_i32 s30, s6, 0x180
	v_lshl_add_u64 v[26:27], s[30:31], 0, v[70:71]
	v_lshlrev_b64 v[30:31], 7, v[26:27]
	v_or_b32_e32 v30, v30, v0
	v_lshl_add_u64 v[34:35], s[30:31], 0, v[72:73]
	v_lshl_add_u64 v[26:27], s[8:9], 0, v[30:31]
	v_lshlrev_b64 v[38:39], 7, v[34:35]
	v_lshl_add_u64 v[30:31], s[10:11], 0, v[30:31]
	v_or_b32_e32 v38, v38, v0
	v_lshl_add_u64 v[42:43], s[30:31], 0, v[74:75]
	v_lshl_add_u64 v[34:35], s[8:9], 0, v[38:39]
	v_lshlrev_b64 v[46:47], 7, v[42:43]
	v_lshl_add_u64 v[38:39], s[10:11], 0, v[38:39]
	v_or_b32_e32 v46, v46, v0
	v_lshl_add_u64 v[50:51], s[30:31], 0, v[76:77]
	v_lshl_add_u64 v[42:43], s[8:9], 0, v[46:47]
	v_lshlrev_b64 v[54:55], 7, v[50:51]
	v_lshl_add_u64 v[46:47], s[10:11], 0, v[46:47]
	v_or_b32_e32 v54, v54, v0
	v_lshl_add_u64 v[58:59], s[30:31], 0, v[78:79]
	v_lshl_add_u64 v[50:51], s[8:9], 0, v[54:55]
	v_lshlrev_b64 v[62:63], 7, v[58:59]
	v_lshl_add_u64 v[54:55], s[10:11], 0, v[54:55]
	v_or_b32_e32 v62, v62, v0
	v_lshl_add_u64 v[58:59], s[8:9], 0, v[62:63]
	v_lshl_add_u64 v[62:63], s[10:11], 0, v[62:63]
	s_or_b32 s2, s6, s16
	s_xor_b64 s[12:13], s[4:5], -1
	s_mov_b64 s[14:15], 0
	s_waitcnt vmcnt(0)
	v_cvt_f32_f16_e32 v6, v2
	v_cvt_f32_f16_sdwa v2, v2 dst_sel:DWORD dst_unused:UNUSED_PAD src0_sel:WORD_1
	v_med3_f32 v6, v6, s70, v223
	v_add_f32_e32 v6, v6, v6
	v_mul_f32_e32 v6, 0x3fb8aa3b, v6
	v_exp_f32_e32 v6, v6
	v_med3_f32 v2, v2, s70, v223
	v_add_f32_e32 v2, v2, v2
	v_mul_f32_e32 v2, 0x3fb8aa3b, v2
	v_add_f32_e32 v7, 1.0, v6
	v_rcp_f32_e32 v8, v7
	v_exp_f32_e32 v7, v2
	s_nop 0
	v_add_f32_e32 v2, 1.0, v7
	v_rcp_f32_e32 v9, v2
	v_pk_add_f32 v[6:7], v[6:7], -1.0 op_sel_hi:[1,0]
	s_nop 0
	v_pk_mul_f32 v[6:7], v[6:7], v[8:9]
	s_nop 0
	v_cvt_pk_f16_f32 v2, v6, v7
	v_cvt_f32_f16_e32 v6, v3
	v_cvt_f32_f16_sdwa v3, v3 dst_sel:DWORD dst_unused:UNUSED_PAD src0_sel:WORD_1
	v_med3_f32 v6, v6, s70, v223
	v_add_f32_e32 v6, v6, v6
	v_mul_f32_e32 v6, 0x3fb8aa3b, v6
	v_exp_f32_e32 v6, v6
	v_med3_f32 v3, v3, s70, v223
	v_add_f32_e32 v3, v3, v3
	v_mul_f32_e32 v3, 0x3fb8aa3b, v3
	v_add_f32_e32 v7, 1.0, v6
	v_rcp_f32_e32 v8, v7
	v_exp_f32_e32 v7, v3
	s_nop 0
	v_add_f32_e32 v3, 1.0, v7
	v_rcp_f32_e32 v9, v3
	v_pk_add_f32 v[6:7], v[6:7], -1.0 op_sel_hi:[1,0]
	s_nop 0
	v_pk_mul_f32 v[6:7], v[6:7], v[8:9]
	s_nop 0
	v_cvt_pk_f16_f32 v3, v6, v7
	v_cvt_f32_f16_e32 v6, v4
	v_cvt_f32_f16_sdwa v4, v4 dst_sel:DWORD dst_unused:UNUSED_PAD src0_sel:WORD_1
	v_med3_f32 v6, v6, s70, v223
	v_add_f32_e32 v6, v6, v6
	v_mul_f32_e32 v6, 0x3fb8aa3b, v6
	v_exp_f32_e32 v6, v6
	v_med3_f32 v4, v4, s70, v223
	v_add_f32_e32 v4, v4, v4
	v_mul_f32_e32 v4, 0x3fb8aa3b, v4
	v_add_f32_e32 v7, 1.0, v6
	v_rcp_f32_e32 v8, v7
	v_exp_f32_e32 v7, v4
	s_nop 0
	v_add_f32_e32 v4, 1.0, v7
	v_rcp_f32_e32 v9, v4
	v_pk_add_f32 v[6:7], v[6:7], -1.0 op_sel_hi:[1,0]
	s_nop 0
	v_pk_mul_f32 v[6:7], v[6:7], v[8:9]
	s_nop 0
	v_cvt_pk_f16_f32 v4, v6, v7
	v_cvt_f32_f16_e32 v6, v5
	v_cvt_f32_f16_sdwa v5, v5 dst_sel:DWORD dst_unused:UNUSED_PAD src0_sel:WORD_1
	v_med3_f32 v6, v6, s70, v223
	v_add_f32_e32 v6, v6, v6
	v_mul_f32_e32 v6, 0x3fb8aa3b, v6
	v_exp_f32_e32 v6, v6
	v_med3_f32 v5, v5, s70, v223
	v_add_f32_e32 v5, v5, v5
	v_mul_f32_e32 v5, 0x3fb8aa3b, v5
	v_add_f32_e32 v7, 1.0, v6
	v_rcp_f32_e32 v8, v7
	v_exp_f32_e32 v7, v5
	s_nop 0
	v_add_f32_e32 v5, 1.0, v7
	v_rcp_f32_e32 v9, v5
	v_pk_add_f32 v[6:7], v[6:7], -1.0 op_sel_hi:[1,0]
	s_nop 0
	v_pk_mul_f32 v[6:7], v[6:7], v[8:9]
	s_nop 0
	v_cvt_pk_f16_f32 v5, v6, v7
	global_load_dwordx4 v[6:9], v[14:15], off offset:3840
	global_load_dwordx4 v[10:13], v[14:15], off offset:3648
	s_waitcnt vmcnt(0)
; #define LAS __attribute__((address_space(3)))
; __device__ __forceinline__ float tanhf_(float x) { const float e = __expf(2.0f * fminf(fmaxf(x, -15.f), 15.f)); return (e - 1.0f) * __builtin_amdgcn_rcpf(e + 1.0f); }
; __device__ __forceinline__ void phase_rwb(const int wvs, const Params& p, LAS unsigned char* lds, int layer) {
;     ...
;     for (int ks = 0; ks < 2; ++ks) { const h8 x = *(const h8*)(P + tok * PP + PC_RL2 + d * 64 + ks * 32 + fq * 8);
; #pragma unroll
;       for (int j = 0; j < 8; ++j) bw[ks][j] = (hf)tanhf_((float)x[j]);
;       ba[ks] = *(const h8*)(P + tok * PP + PC_RL2 + 128 + d * 64 + ks * 32 + fq * 8); }
;     { h8 sw[6], sa[6];
; #pragma unroll
;       for (int j = 0; j < 6; ++j) { const int idx = tid + 512 * j; const size_t wo = ((size_t)d * 384 + (idx >> 3)) * 64 + (idx & 7) * 8; sw[j] = *(const h8*)(wupT + wo); sa[j] = *(const h8*)(aupT + wo); }
;       __syncthreads();
; #pragma unroll
;       for (int j = 0; j < 6; ++j) { const int idx = tid + 512 * j; *(LAS h8*)(lds + (idx >> 3) * 144 + (idx & 7) * 16) = sw[j]; *(LAS h8*)(lds + 55296 + (idx >> 3) * 144 + (idx & 7) * 16) = sa[j]; }
;       __syncthreads(); }
;     const float* w0 = p.in[I_W0] + (layer * 2 + d) * 384; const float* a0 = p.in[I_A0] + (layer * 2 + d) * 384;
; #pragma unroll 2
;     for (int nt = 0; nt < 24; ++nt) { f32x4 aw = {0.f, 0.f, 0.f, 0.f}, aa = {0.f, 0.f, 0.f, 0.f};
;       const int n4 = nt * 16 + fq * 4; const f32x4 w04 = *(const f32x4*)(w0 + n4), a04 = *(const f32x4*)(a0 + n4);
	v_cvt_f32_f16_e32 v16, v10
	v_cvt_f32_f16_sdwa v10, v10 dst_sel:DWORD dst_unused:UNUSED_PAD src0_sel:WORD_1
	global_load_dwordx4 v[30:33], v[30:31], off
	v_med3_f32 v16, v16, s70, v223
	v_add_f32_e32 v16, v16, v16
	v_mul_f32_e32 v16, 0x3fb8aa3b, v16
	v_exp_f32_e32 v16, v16
	v_med3_f32 v10, v10, s70, v223
	v_add_f32_e32 v10, v10, v10
	v_mul_f32_e32 v10, 0x3fb8aa3b, v10
	v_add_f32_e32 v17, 1.0, v16
	v_rcp_f32_e32 v18, v17
	v_exp_f32_e32 v17, v10
	global_load_dwordx4 v[34:37], v[34:35], off
	v_add_f32_e32 v10, 1.0, v17
	v_rcp_f32_e32 v19, v10
	v_pk_add_f32 v[16:17], v[16:17], -1.0 op_sel_hi:[1,0]
	global_load_dwordx4 v[38:41], v[38:39], off
	v_pk_mul_f32 v[16:17], v[16:17], v[18:19]
	s_nop 0
	v_cvt_pk_f16_f32 v10, v16, v17
	v_cvt_f32_f16_e32 v16, v11
	v_cvt_f32_f16_sdwa v11, v11 dst_sel:DWORD dst_unused:UNUSED_PAD src0_sel:WORD_1
	global_load_dwordx4 v[42:45], v[42:43], off
	v_med3_f32 v16, v16, s70, v223
	v_add_f32_e32 v16, v16, v16
	v_mul_f32_e32 v16, 0x3fb8aa3b, v16
	v_exp_f32_e32 v16, v16
	v_med3_f32 v11, v11, s70, v223
	v_add_f32_e32 v11, v11, v11
	v_mul_f32_e32 v11, 0x3fb8aa3b, v11
	v_add_f32_e32 v17, 1.0, v16
	v_rcp_f32_e32 v18, v17
	v_exp_f32_e32 v17, v11
	global_load_dwordx4 v[46:49], v[46:47], off
	v_add_f32_e32 v11, 1.0, v17
	v_rcp_f32_e32 v19, v11
	v_pk_add_f32 v[16:17], v[16:17], -1.0 op_sel_hi:[1,0]
	global_load_dwordx4 v[50:53], v[50:51], off
	v_pk_mul_f32 v[16:17], v[16:17], v[18:19]
	s_nop 0
	v_cvt_pk_f16_f32 v11, v16, v17
	v_cvt_f32_f16_e32 v16, v12
	v_cvt_f32_f16_sdwa v12, v12 dst_sel:DWORD dst_unused:UNUSED_PAD src0_sel:WORD_1
	global_load_dwordx4 v[54:57], v[54:55], off
	v_med3_f32 v16, v16, s70, v223
	v_add_f32_e32 v16, v16, v16
	v_mul_f32_e32 v16, 0x3fb8aa3b, v16
	v_exp_f32_e32 v16, v16
	v_med3_f32 v12, v12, s70, v223
	v_add_f32_e32 v12, v12, v12
	v_mul_f32_e32 v12, 0x3fb8aa3b, v12
	v_add_f32_e32 v17, 1.0, v16
	v_rcp_f32_e32 v18, v17
	v_exp_f32_e32 v17, v12
	global_load_dwordx4 v[58:61], v[58:59], off
	v_add_f32_e32 v12, 1.0, v17
	v_rcp_f32_e32 v19, v12
	v_pk_add_f32 v[16:17], v[16:17], -1.0 op_sel_hi:[1,0]
	global_load_dwordx4 v[62:65], v[62:63], off
	v_pk_mul_f32 v[16:17], v[16:17], v[18:19]
	s_nop 0
	v_cvt_pk_f16_f32 v12, v16, v17
	v_cvt_f32_f16_e32 v16, v13
	v_cvt_f32_f16_sdwa v13, v13 dst_sel:DWORD dst_unused:UNUSED_PAD src0_sel:WORD_1
	global_load_dwordx4 v[26:29], v[26:27], off
	v_med3_f32 v16, v16, s70, v223
	v_add_f32_e32 v16, v16, v16
	v_mul_f32_e32 v16, 0x3fb8aa3b, v16
	v_exp_f32_e32 v16, v16
	v_med3_f32 v13, v13, s70, v223
	v_add_f32_e32 v13, v13, v13
	v_mul_f32_e32 v13, 0x3fb8aa3b, v13
	v_add_f32_e32 v17, 1.0, v16
	v_rcp_f32_e32 v18, v17
	v_exp_f32_e32 v17, v13
	s_nop 0
	v_add_f32_e32 v13, 1.0, v17
	v_rcp_f32_e32 v19, v13
	v_pk_add_f32 v[16:17], v[16:17], -1.0 op_sel_hi:[1,0]
	s_nop 0
	v_pk_mul_f32 v[16:17], v[16:17], v[18:19]
	v_lshl_add_u64 v[18:19], s[30:31], 0, v[68:69]
	v_lshlrev_b64 v[22:23], 7, v[18:19]
	v_or_b32_e32 v22, v22, v0
	v_lshl_add_u64 v[18:19], s[8:9], 0, v[22:23]
	v_cvt_pk_f16_f32 v13, v16, v17
	global_load_dwordx4 v[14:17], v[14:15], off offset:3904
	v_lshl_add_u64 v[22:23], s[10:11], 0, v[22:23]
	global_load_dwordx4 v[18:21], v[18:19], off
	s_mul_i32 s30, s2, 0x180
	global_load_dwordx4 v[22:25], v[22:23], off
	s_lshl_b64 s[4:5], s[30:31], 2
	v_min_u32_e32 v104, 0x5f, v193
	v_lshlrev_b32_e32 v104, 4, v104
	v_and_b32_e32 v107, 48, v193
	v_sub_u32_e32 v108, v104, v107
	v_ashrrev_i32_e32 v109, 31, v108
	v_lshl_add_u64 v[110:111], v[84:85], 0, s[4:5]
	v_lshl_add_u64 v[110:111], v[110:111], 0, v[108:109]
	global_load_dwordx4 v[96:99], v[110:111], off
	v_lshl_add_u64 v[110:111], v[82:83], 0, s[4:5]
	v_lshl_add_u64 v[110:111], v[110:111], 0, v[108:109]
	global_load_dwordx4 v[100:103], v[110:111], off
	s_barrier
	s_waitcnt vmcnt(3)
	ds_write_b128 v87, v[18:21]
	s_waitcnt vmcnt(2)
	ds_write_b128 v87, v[22:25] offset:55296
	ds_write_b128 v88, v[26:29]
	ds_write_b128 v88, v[30:33] offset:55296
	ds_write_b128 v89, v[34:37]
	ds_write_b128 v89, v[38:41] offset:55296
	ds_write_b128 v90, v[42:45]
	ds_write_b128 v90, v[46:49] offset:55296
	ds_write_b128 v91, v[50:53]
	ds_write_b128 v91, v[54:57] offset:55296
	ds_write_b128 v92, v[58:61]
	ds_write_b128 v92, v[62:65] offset:55296
	v_mov_b32_e32 v18, 0x300
	v_mad_u64_u32 v[26:27], s[4:5], s6, v18, v[80:81]
	s_lshl_b64 s[4:5], s[30:31], 2
	s_nop 0
	v_lshl_add_u64 v[28:29], v[82:83], 0, s[4:5]
	v_lshl_add_u64 v[30:31], v[84:85], 0, s[4:5]
	v_mov_b32_e32 v32, v86
	v_min_u32_e32 v104, 0x5f, v193
	v_lshlrev_b32_e32 v104, 4, v104
	v_and_b32_e32 v106, 48, v193
	v_add_u32_e32 v105, 0x1b800, v104
	v_add_u32_e32 v106, 0x1b800, v106
	s_waitcnt vmcnt(0)
	ds_write_b128 v105, v[96:99]
	ds_write_b128 v105, v[100:103] offset:1536
	s_waitcnt lgkmcnt(0)
	s_barrier
	v_readfirstlane_b32 s4, v193
	s_nop 0
	s_cmp_lt_u32 s4, 0x100
	s_cbranch_scc1 .Lrwb_go
	s_sleep 12
